# v17 + P3 next-unit Q/K/V+dec prefetch issued right after the unit-top barrier (state waits recounted 17/16/15/14)
# baseline (speedup 1.0000x reference)
; #define LAS __attribute__((address_space(3)))
; __device__ __forceinline__ f32x4 mfma16(bf16x8 a, bf16x8 b, f32x4 c) { return __builtin_amdgcn_mfma_f32_16x16x32_bf16(a, b, c, 0, 0, 0); }
; #define LBAR() asm volatile("s_waitcnt lgkmcnt(0)\n\ts_barrier" ::: "memory")
; #define OPQ_ALL() do { asm volatile("" : "+v"(g), "+v"(l15), "+v"(q4), "+v"(p)); } while (0)
; __device__ __forceinline__ void ret_phase(const Params& P, LAS unsigned char* lds, int tid, int lane, int wave, int bid, int G) {
;     ...
;         const int gc = u >> 2, h = u & 3; const size_t tokc = (size_t)gc * 128;
;         const float lgf2 = -__expf(P.dec_f[h]) * LOG2E, lgb2 = -__expf(P.dec_b[h]) * LOG2E;
; #pragma unroll
;         for (int i = 0; i < 4; ++i) { const int idx = tid + 512 * i; const unsigned d = off256(idx >> 4, idx & 15);
;             *(LAS u32x4*)(Qt + d) = rq[i]; *(LAS u32x4*)(Kt + d) = rk[i]; *(LAS u32x4*)(Vt + d) = rv[i]; }
;         LBAR();
;         const bf16_t* Sf = ST + ((size_t)(gc * 4 + h) * 2 + 0) * 16384; const bf16_t* Sb = Sf + 16384;
;         u32x4 rsf[2], rsb[2];
; #pragma unroll
;         for (int j = 0; j < 2; ++j) { const int idx = tid + 512 * j; rsf[j] = *(const u32x4*)((const unsigned char*)Sf + 16 * idx); rsb[j] = *(const u32x4*)((const unsigned char*)Sb + 16 * idx); }
;         OPQ_ALL();
;         bf16x8 qf[4];
; #pragma unroll
;         for (int ks = 0; ks < 4; ++ks) qf[ks] = *(const LAS bf16x8*)(Qt + off256(w16 + l15, 4 * ks + g));
;         {
;             const int n = w16 + l15;
;             f32x4 sa[8];
; #pragma unroll
;             for (int mt = 0; mt < 8; ++mt) {
;                 f32x4 a = (f32x4){0.f, 0.f, 0.f, 0.f};
; #pragma unroll
;                 for (int ks = 0; ks < 4; ++ks) a = mfma16(*(const LAS bf16x8*)(Kt + off256(16 * mt + l15, 4 * ks + g)), qf[ks], a);
;                 sa[mt] = a; }
.Lp3_common:
	ds_write_b128 v50, v[6:9]
	ds_write_b128 v50, v[2:5] offset:32768
	ds_write_b128 v51, v[10:13]
	v_add_u32_e32 v51, 0, v109
	s_ashr_i32 s27, s26, 31
	s_ashr_i32 s40, s26, 2
	ds_write_b128 v51, v[14:17]
	ds_write_b128 v51, v[22:25] offset:32768
	v_add_u32_e32 v51, s48, v109
	s_lshl_b64 s[0:1], s[26:27], 16
	ds_write_b128 v51, v[18:21]
	ds_write_b128 v50, v[30:33] offset:16384
	ds_write_b128 v50, v[26:29] offset:49152
	ds_write_b128 v127, v[34:37]
	v_add_u32_e32 v50, 0, v111
	s_add_u32 s0, s44, s0
	ds_write_b128 v50, v[38:41]
	ds_write_b128 v50, v[46:49] offset:32768
	v_add_u32_e32 v50, s48, v111
	s_addc_u32 s1, s45, s1
	ds_write_b128 v50, v[42:45]
	v_lshl_add_u64 v[50:51], s[0:1], 0, v[116:117]
	v_add_co_u32_e32 v52, vcc, s47, v50
	s_waitcnt lgkmcnt(0)
	s_barrier
	v_lshl_add_u32 v214, s57, 7, v1
	v_ashrrev_i32_e32 v215, 31, v214
	v_lshl_add_u64 v[214:215], v[214:215], 2, s[62:63]
	global_load_dword v205, v[214:215], off
	global_load_dword v206, v[214:215], off offset:64
	global_load_dword v207, v[214:215], off offset:128
	global_load_dword v208, v[214:215], off offset:192
	global_load_dword v209, v[214:215], off offset:256
	global_load_dword v210, v[214:215], off offset:320
	global_load_dword v211, v[214:215], off offset:384
	global_load_dword v212, v[214:215], off offset:448
	s_add_i32 s4, s26, s3
	s_cmpk_gt_i32 s4, 0x9ff
	s_cselect_b32 s4, s26, s4
	s_ashr_i32 s0, s4, 2
	s_ashr_i32 s1, s0, 31
	s_lshl_b32 s5, s4, 7
	s_lshl_b64 s[0:1], s[0:1], 16
	s_and_b32 s5, s5, 0x180
	s_or_b32 s0, s0, s5
	s_and_b32 s4, s4, 3
	s_lshl_b32 s4, s4, 2
	s_cmpk_lt_i32 s40, 0x200
	s_nop 0
	v_addc_co_u32_e32 v53, vcc, 0, v51, vcc
	global_load_dwordx4 v[68:71], v[50:51], off
	global_load_dwordx4 v[76:79], v[52:53], off
	v_add_co_u32_e32 v52, vcc, s49, v50
	v_mul_f32_e32 v104, 0x3fb8aa3b, v104
	s_nop 0
	v_addc_co_u32_e32 v53, vcc, 0, v51, vcc
	v_add_co_u32_e32 v50, vcc, s50, v50
	v_mul_f32_e32 v105, 0x3fb8aa3b, v105
	s_nop 0
	v_addc_co_u32_e32 v51, vcc, 0, v51, vcc
	global_load_dwordx4 v[84:87], v[52:53], off
	global_load_dwordx4 v[92:95], v[50:51], off
	v_mov_b32_e32 v35, s1
	v_or_b32_e32 v34, s0, v106
	v_mov_b32_e32 v3, s1
	v_or_b32_e32 v2, v34, v108
	v_mov_b32_e32 v13, s1
	v_or_b32_e32 v12, v34, v110
	v_mov_b32_e32 v27, s1
	v_or_b32_e32 v26, v34, v112
	v_lshl_add_u64 v[34:35], v[34:35], 0, v[114:115]
	v_lshlrev_b64 v[10:11], 1, v[2:3]
	v_lshlrev_b64 v[18:19], 1, v[12:13]
	v_lshlrev_b64 v[36:37], 1, v[26:27]
	v_lshlrev_b64 v[42:43], 1, v[34:35]
	v_lshl_add_u64 v[2:3], s[10:11], 0, v[10:11]
	v_lshl_add_u64 v[4:5], s[12:13], 0, v[10:11]
	v_lshl_add_u64 v[10:11], s[14:15], 0, v[10:11]
	v_lshl_add_u64 v[14:15], s[10:11], 0, v[18:19]
	v_lshl_add_u64 v[20:21], s[12:13], 0, v[18:19]
	v_lshl_add_u64 v[18:19], s[14:15], 0, v[18:19]
	v_lshl_add_u64 v[26:27], s[10:11], 0, v[36:37]
	v_lshl_add_u64 v[28:29], s[12:13], 0, v[36:37]
	v_lshl_add_u64 v[36:37], s[14:15], 0, v[36:37]
	v_lshl_add_u64 v[38:39], s[10:11], 0, v[42:43]
	v_lshl_add_u64 v[44:45], s[12:13], 0, v[42:43]
	v_lshl_add_u64 v[42:43], s[14:15], 0, v[42:43]
	global_load_dwordx4 v[6:9], v[2:3], off
	s_nop 0
	global_load_dwordx4 v[2:5], v[4:5], off
	s_nop 0
	global_load_dwordx4 v[10:13], v[10:11], off
	s_nop 0
	global_load_dwordx4 v[14:17], v[14:15], off
	s_nop 0
	global_load_dwordx4 v[22:25], v[20:21], off
	s_nop 0
	global_load_dwordx4 v[18:21], v[18:19], off
	s_nop 0
	global_load_dwordx4 v[30:33], v[26:27], off
	s_nop 0
	global_load_dwordx4 v[26:29], v[28:29], off
	s_nop 0
	global_load_dwordx4 v[34:37], v[36:37], off
	s_nop 0
	global_load_dwordx4 v[38:41], v[38:39], off
	s_nop 0
	global_load_dwordx4 v[46:49], v[44:45], off
	s_nop 0
	global_load_dwordx4 v[42:45], v[42:43], off
	v_mov_b32_e32 v218, s4
	global_load_dword v216, v218, s[58:59]
	global_load_dword v217, v218, s[60:61]
	v_exp_f32_e32 v104, v104
	v_lshlrev_b32_e32 v50, 2, v1
	v_add_u32_e32 v119, s46, v1
	v_and_b32_e32 v66, 12, v50
	v_bfe_u32 v67, v1, 2, 2
	v_lshlrev_b32_e32 v135, 8, v119
	v_bitop3_b32 v50, v66, v118, v67 bitop3:0x36
	v_add_u32_e32 v52, 4, v118
	v_add_u32_e32 v100, 0, v135
	v_lshlrev_b32_e32 v50, 4, v50
	v_bitop3_b32 v52, v66, v52, v67 bitop3:0x36
	v_add_u32_e32 v51, v100, v50
	v_lshlrev_b32_e32 v72, 4, v52
	v_add_u32_e32 v52, v100, v72
	ds_read_b128 v[58:61], v51
	ds_read_b128 v[54:57], v52
	v_add_u32_e32 v51, 8, v118
	v_lshl_add_u32 v122, v1, 8, 0
	v_bitop3_b32 v51, v66, v51, v67 bitop3:0x36
	v_add_u32_e32 v156, v122, v50
	v_lshlrev_b32_e32 v80, 4, v51
	ds_read_b128 v[50:53], v156 offset:32768
	v_add_u32_e32 v157, v122, v72
	ds_read_b128 v[72:75], v157 offset:32768
	v_add_u32_e32 v62, v100, v80
	ds_read_b128 v[62:65], v62
	s_waitcnt lgkmcnt(2)
	v_mfma_f32_16x16x32_bf16 v[50:53], v[50:53], v[58:61], 0
	v_add_u32_e32 v158, v122, v80
	v_add_u32_e32 v96, 12, v118
	ds_read_b128 v[80:83], v158 offset:32768
	ds_read_b128 v[88:91], v156 offset:36864
	s_waitcnt lgkmcnt(3)
	v_mfma_f32_16x16x32_bf16 v[72:75], v[72:75], v[54:57], v[50:53]
	v_bitop3_b32 v96, v66, v96, v67 bitop3:0x36
	v_lshlrev_b32_e32 v123, 4, v96
	ds_read_b128 v[96:99], v157 offset:36864
	v_add_u32_e32 v50, v100, v123
	v_add_u32_e32 v159, v122, v123
	ds_read_b128 v[50:53], v50
	ds_read_b128 v[100:103], v158 offset:36864
	s_waitcnt lgkmcnt(4)
	v_mfma_f32_16x16x32_bf16 v[72:75], v[80:83], v[62:65], v[72:75]
	ds_read_b128 v[80:83], v159 offset:32768
	ds_read_b128 v[122:125], v159 offset:36864
	s_waitcnt lgkmcnt(1)
	v_mfma_f32_16x16x32_bf16 v[136:139], v[80:83], v[50:53], v[72:75]
	v_mfma_f32_16x16x32_bf16 v[72:75], v[88:91], v[58:61], 0
	v_mfma_f32_16x16x32_bf16 v[72:75], v[96:99], v[54:57], v[72:75]
	v_mfma_f32_16x16x32_bf16 v[72:75], v[100:103], v[62:65], v[72:75]
	s_waitcnt lgkmcnt(0)
; __device__ __forceinline__ unsigned cvt_pk_bf16(float lo, float hi) { unsigned r; asm volatile("v_cvt_pk_bf16_f32 %0, %1, %2" : "=v"(r) : "v"(lo), "v"(hi)); return r; }
; #define LAS __attribute__((address_space(3)))
; __device__ __forceinline__ f32x4 mfma16(bf16x8 a, bf16x8 b, f32x4 c) { return __builtin_amdgcn_mfma_f32_16x16x32_bf16(a, b, c, 0, 0, 0); }
; __device__ __forceinline__ void ret_phase(const Params& P, LAS unsigned char* lds, int tid, int lane, int wave, int bid, int G) {
;     ...
;             for (int mt = 0; mt < 8; ++mt) {
;                 f32x4 a = (f32x4){0.f, 0.f, 0.f, 0.f};
; #pragma unroll
;                 for (int ks = 0; ks < 4; ++ks) a = mfma16(*(const LAS bf16x8*)(Kt + off256(16 * mt + l15, 4 * ks + g)), qf[ks], a);
;                 sa[mt] = a; }
; #pragma unroll
;             for (int mt = 0; mt < 8; ++mt) {
;                 const f32x4 a = sa[mt];
;                 float e[4];
; #pragma unroll
;                 for (int i = 0; i < 4; ++i) { const int m = 16 * mt + 4 * g + i, df = n - m; const float f = __builtin_amdgcn_exp2f(df >= 0 ? lgf2 * (float)df : lgb2 * (float)(-df)); e[i] = a[i] * f; }
;                 u32x2 w; w.x = cvt_pk_bf16(e[0], e[1]); w.y = cvt_pk_bf16(e[2], e[3]);
;                 *(LAS u32x2*)(Pt + off256(n, 2 * mt + (g >> 1)) + 8 * (g & 1)) = w;
;             }
	v_mfma_f32_16x16x32_bf16 v[122:125], v[122:125], v[50:53], v[72:75]
	s_nop 5
	ds_read_b128 v[72:75], v156 offset:40960
	ds_read_b128 v[80:83], v156 offset:45056
	ds_read_b128 v[88:91], v157 offset:40960
	ds_read_b128 v[96:99], v157 offset:45056
	s_waitcnt lgkmcnt(3)
	v_mfma_f32_16x16x32_bf16 v[72:75], v[72:75], v[58:61], 0
	s_waitcnt lgkmcnt(1)
	v_mfma_f32_16x16x32_bf16 v[72:75], v[88:91], v[54:57], v[72:75]
	ds_read_b128 v[88:91], v158 offset:40960
	ds_read_b128 v[100:103], v158 offset:45056
	s_waitcnt lgkmcnt(1)
	v_mfma_f32_16x16x32_bf16 v[72:75], v[88:91], v[62:65], v[72:75]
	ds_read_b128 v[88:91], v159 offset:40960
	ds_read_b128 v[140:143], v159 offset:45056
	s_waitcnt lgkmcnt(1)
	v_mfma_f32_16x16x32_bf16 v[144:147], v[88:91], v[50:53], v[72:75]
	v_mfma_f32_16x16x32_bf16 v[72:75], v[80:83], v[58:61], 0
	v_mfma_f32_16x16x32_bf16 v[72:75], v[96:99], v[54:57], v[72:75]
	v_mfma_f32_16x16x32_bf16 v[72:75], v[100:103], v[62:65], v[72:75]
	s_waitcnt lgkmcnt(0)
	v_mfma_f32_16x16x32_bf16 v[100:103], v[140:143], v[50:53], v[72:75]
	s_nop 5
	ds_read_b128 v[72:75], v156 offset:49152
	ds_read_b128 v[80:83], v156 offset:53248
	ds_read_b128 v[88:91], v157 offset:49152
	ds_read_b128 v[140:143], v157 offset:53248
	s_waitcnt lgkmcnt(3)
	v_mfma_f32_16x16x32_bf16 v[72:75], v[72:75], v[58:61], 0
	s_waitcnt lgkmcnt(1)
	v_mfma_f32_16x16x32_bf16 v[72:75], v[88:91], v[54:57], v[72:75]
	ds_read_b128 v[88:91], v158 offset:49152
	ds_read_b128 v[148:151], v158 offset:53248
	s_waitcnt lgkmcnt(1)
	v_mfma_f32_16x16x32_bf16 v[72:75], v[88:91], v[62:65], v[72:75]
	ds_read_b128 v[88:91], v159 offset:49152
	ds_read_b128 v[152:155], v159 offset:53248
	s_waitcnt lgkmcnt(1)
	v_mfma_f32_16x16x32_bf16 v[96:99], v[88:91], v[50:53], v[72:75]
	v_mfma_f32_16x16x32_bf16 v[72:75], v[80:83], v[58:61], 0
	v_mfma_f32_16x16x32_bf16 v[72:75], v[140:143], v[54:57], v[72:75]
	v_mfma_f32_16x16x32_bf16 v[72:75], v[148:151], v[62:65], v[72:75]
	s_waitcnt lgkmcnt(0)
	v_mfma_f32_16x16x32_bf16 v[88:91], v[152:155], v[50:53], v[72:75]
	s_nop 5
	ds_read_b128 v[72:75], v156 offset:57344
	ds_read_b128 v[140:143], v156 offset:61440
	ds_read_b128 v[80:83], v157 offset:57344
	ds_read_b128 v[148:151], v157 offset:61440
	s_waitcnt lgkmcnt(3)
	v_mfma_f32_16x16x32_bf16 v[72:75], v[72:75], v[58:61], 0
	s_waitcnt lgkmcnt(1)
	v_mfma_f32_16x16x32_bf16 v[72:75], v[80:83], v[54:57], v[72:75]
	ds_read_b128 v[80:83], v158 offset:57344
	ds_read_b128 v[152:155], v158 offset:61440
	s_waitcnt lgkmcnt(1)
	v_mfma_f32_16x16x32_bf16 v[72:75], v[80:83], v[62:65], v[72:75]
	ds_read_b128 v[80:83], v159 offset:57344
	ds_read_b128 v[156:159], v159 offset:61440
	s_waitcnt lgkmcnt(1)
	v_mfma_f32_16x16x32_bf16 v[80:83], v[80:83], v[50:53], v[72:75]
	v_mfma_f32_16x16x32_bf16 v[72:75], v[140:143], v[58:61], 0
	v_lshlrev_b32_e32 v142, 2, v118
	v_sub_u32_e32 v143, v119, v142
	v_exp_f32_e32 v140, v105
	v_mfma_f32_16x16x32_bf16 v[72:75], v[148:151], v[54:57], v[72:75]
	v_sub_u32_e32 v148, 0, v143
	v_max_i32_e32 v148, v143, v148
	v_cvt_f32_u32_e32 v148, v148
	v_lshlrev_b32_e32 v141, 3, v118
	v_mul_f32_e32 v105, 0xbfb8aa3b, v104
	v_mul_f32_e32 v104, 0xbfb8aa3b, v140
	v_and_b32_e32 v141, 8, v141
	v_cmp_gt_i32_e32 vcc, 0, v143
	v_add3_u32 v135, s51, v135, v141
	v_lshrrev_b32_e32 v140, 1, v118
	v_cndmask_b32_e32 v141, v105, v104, vcc
	v_mul_f32_e32 v141, v141, v148
	v_xad_u32 v148, v142, -1, v119
	v_sub_u32_e32 v149, 0, v148
	v_max_i32_e32 v149, v148, v149
	v_cvt_f32_u32_e32 v149, v149
	v_cmp_gt_i32_e32 vcc, 0, v148
	v_exp_f32_e32 v141, v141
	v_mfma_f32_16x16x32_bf16 v[72:75], v[152:155], v[62:65], v[72:75]
	v_cndmask_b32_e32 v148, v105, v104, vcc
	v_mul_f32_e32 v148, v148, v149
	v_or_b32_e32 v149, 2, v142
	v_or_b32_e32 v142, 3, v142
	v_sub_u32_e32 v149, v119, v149
	v_sub_u32_e32 v119, v119, v142
	v_sub_u32_e32 v142, 0, v119
	v_sub_u32_e32 v150, 0, v149
	v_max_i32_e32 v142, v119, v142
	v_max_i32_e32 v150, v149, v150
	v_cvt_f32_u32_e32 v142, v142
	v_cvt_f32_u32_e32 v150, v150
	v_cmp_gt_i32_e32 vcc, 0, v149
	v_exp_f32_e32 v148, v148
	v_mul_f32_e32 v136, v141, v136
	v_cndmask_b32_e32 v149, v105, v104, vcc
	v_cmp_gt_i32_e32 vcc, 0, v119
	v_mul_f32_e32 v149, v149, v150
	v_exp_f32_e32 v149, v149
	v_cndmask_b32_e32 v119, v105, v104, vcc
	v_mul_f32_e32 v119, v119, v142
	v_exp_f32_e32 v119, v119
	v_mul_f32_e32 v137, v148, v137
	v_mul_f32_e32 v138, v149, v138
	v_cvt_pk_bf16_f32 v136, v136, v137
	v_mul_f32_e32 v119, v119, v139
	v_cvt_pk_bf16_f32 v137, v138, v119
	v_bitop3_b32 v119, v66, v140, v67 bitop3:0x36
	v_lshl_add_u32 v119, v119, 4, v135
	ds_write_b64 v119, v[136:137]
	v_subrev_u32_e32 v136, 17, v143
	v_sub_u32_e32 v137, 17, v143
	v_max_i32_e32 v137, v136, v137
	v_add_u32_e32 v138, -16, v143
	v_cvt_f32_u32_e32 v137, v137
	v_cmp_gt_i32_e32 vcc, 0, v138
	v_sub_u32_e32 v139, 16, v143
	v_max_i32_e32 v139, v138, v139
	v_cndmask_b32_e32 v119, v105, v104, vcc
	v_cmp_gt_i32_e32 vcc, 0, v136
	v_sub_u32_e32 v138, 18, v143
	v_cvt_f32_u32_e32 v139, v139
	v_cndmask_b32_e32 v136, v105, v104, vcc
	v_mul_f32_e32 v136, v136, v137
	v_subrev_u32_e32 v137, 18, v143
	v_max_i32_e32 v138, v137, v138
	v_cvt_f32_u32_e32 v138, v138
	v_cmp_gt_i32_e32 vcc, 0, v137
	v_mul_f32_e32 v119, v119, v139
	v_sub_u32_e32 v139, 19, v143
	v_cndmask_b32_e32 v137, v105, v104, vcc
	v_mul_f32_e32 v137, v137, v138
	v_subrev_u32_e32 v138, 19, v143
	v_max_i32_e32 v139, v138, v139
	v_cvt_f32_u32_e32 v139, v139
	v_exp_f32_e32 v119, v119
	v_exp_f32_e32 v136, v136
	v_cmp_gt_i32_e32 vcc, 0, v138
	v_exp_f32_e32 v137, v137
	v_mul_f32_e32 v119, v119, v122
	v_cndmask_b32_e32 v138, v105, v104, vcc
	v_mul_f32_e32 v138, v138, v139
	v_exp_f32_e32 v138, v138
	v_mul_f32_e32 v122, v136, v123
; __device__ __forceinline__ unsigned cvt_pk_bf16(float lo, float hi) { unsigned r; asm volatile("v_cvt_pk_bf16_f32 %0, %1, %2" : "=v"(r) : "v"(lo), "v"(hi)); return r; }
; #define LAS __attribute__((address_space(3)))
; __device__ __forceinline__ void ret_phase(const Params& P, LAS unsigned char* lds, int tid, int lane, int wave, int bid, int G) {
;     ...
;             for (int mt = 0; mt < 8; ++mt) {
;                 const f32x4 a = sa[mt];
;                 float e[4];
; #pragma unroll
;                 for (int i = 0; i < 4; ++i) { const int m = 16 * mt + 4 * g + i, df = n - m; const float f = __builtin_amdgcn_exp2f(df >= 0 ? lgf2 * (float)df : lgb2 * (float)(-df)); e[i] = a[i] * f; }
;                 u32x2 w; w.x = cvt_pk_bf16(e[0], e[1]); w.y = cvt_pk_bf16(e[2], e[3]);
;                 *(LAS u32x2*)(Pt + off256(n, 2 * mt + (g >> 1)) + 8 * (g & 1)) = w;
;             }
	v_cvt_pk_bf16_f32 v122, v119, v122
	v_add_u32_e32 v119, 2, v140
	v_mul_f32_e32 v123, v137, v124
	v_bitop3_b32 v119, v66, v119, v67 bitop3:0x36
	v_mul_f32_e32 v124, v138, v125
	v_cvt_pk_bf16_f32 v123, v123, v124
	v_lshl_add_u32 v119, v119, 4, v135
	ds_write_b64 v119, v[122:123]
	v_subrev_u32_e32 v122, 33, v143
	v_sub_u32_e32 v123, 33, v143
	v_max_i32_e32 v123, v122, v123
	v_subrev_u32_e32 v124, 32, v143
	v_cvt_f32_u32_e32 v123, v123
	v_cmp_gt_i32_e32 vcc, 0, v124
	v_sub_u32_e32 v125, 32, v143
	v_max_i32_e32 v125, v124, v125
	v_cndmask_b32_e32 v119, v105, v104, vcc
	v_cmp_gt_i32_e32 vcc, 0, v122
	v_sub_u32_e32 v124, 34, v143
	v_cvt_f32_u32_e32 v125, v125
	v_cndmask_b32_e32 v122, v105, v104, vcc
	v_mul_f32_e32 v122, v122, v123
	v_subrev_u32_e32 v123, 34, v143
	v_max_i32_e32 v124, v123, v124
	v_cvt_f32_u32_e32 v124, v124
	v_cmp_gt_i32_e32 vcc, 0, v123
	v_mul_f32_e32 v119, v119, v125
	v_sub_u32_e32 v125, 35, v143
	v_cndmask_b32_e32 v123, v105, v104, vcc
	v_mul_f32_e32 v123, v123, v124
	v_subrev_u32_e32 v124, 35, v143
	v_max_i32_e32 v125, v124, v125
	v_cvt_f32_u32_e32 v125, v125
	v_exp_f32_e32 v119, v119
	v_exp_f32_e32 v122, v122
	v_cmp_gt_i32_e32 vcc, 0, v124
	v_exp_f32_e32 v123, v123
	v_mul_f32_e32 v119, v119, v144
	v_cndmask_b32_e32 v124, v105, v104, vcc
	v_mul_f32_e32 v124, v124, v125
	v_exp_f32_e32 v124, v124
	v_mul_f32_e32 v122, v122, v145
	v_cvt_pk_bf16_f32 v122, v119, v122
	v_add_u32_e32 v119, 4, v140
	v_mul_f32_e32 v123, v123, v146
	v_bitop3_b32 v119, v66, v119, v67 bitop3:0x36
	v_mul_f32_e32 v124, v124, v147
	v_cvt_pk_bf16_f32 v123, v123, v124
	v_lshl_add_u32 v119, v119, 4, v135
	ds_write_b64 v119, v[122:123]
	v_subrev_u32_e32 v122, 49, v143
	v_sub_u32_e32 v123, 49, v143
	v_max_i32_e32 v123, v122, v123
	v_subrev_u32_e32 v124, 48, v143
	v_cvt_f32_u32_e32 v123, v123
	v_cmp_gt_i32_e32 vcc, 0, v124
	v_sub_u32_e32 v125, 48, v143
	v_max_i32_e32 v125, v124, v125
	v_cndmask_b32_e32 v119, v105, v104, vcc
	v_cmp_gt_i32_e32 vcc, 0, v122
	v_sub_u32_e32 v124, 50, v143
	v_cvt_f32_u32_e32 v125, v125
	v_cndmask_b32_e32 v122, v105, v104, vcc
	v_mul_f32_e32 v122, v122, v123
	v_subrev_u32_e32 v123, 50, v143
	v_max_i32_e32 v124, v123, v124
	v_cvt_f32_u32_e32 v124, v124
	v_cmp_gt_i32_e32 vcc, 0, v123
	v_mul_f32_e32 v119, v119, v125
	v_sub_u32_e32 v125, 51, v143
	v_cndmask_b32_e32 v123, v105, v104, vcc
	v_mul_f32_e32 v123, v123, v124
	v_subrev_u32_e32 v124, 51, v143
	v_max_i32_e32 v125, v124, v125
	v_cvt_f32_u32_e32 v125, v125
	v_cmp_gt_i32_e32 vcc, 0, v124
	v_exp_f32_e32 v119, v119
	v_exp_f32_e32 v122, v122
	v_cndmask_b32_e32 v124, v105, v104, vcc
	v_exp_f32_e32 v123, v123
	v_mul_f32_e32 v124, v124, v125
	v_exp_f32_e32 v124, v124
	v_mul_f32_e32 v100, v119, v100
	v_mul_f32_e32 v101, v122, v101
	v_mul_f32_e32 v102, v123, v102
	v_mul_f32_e32 v103, v124, v103
	v_cvt_pk_bf16_f32 v100, v100, v101
	v_cvt_pk_bf16_f32 v101, v102, v103
	v_add_u32_e32 v102, 6, v140
	v_bitop3_b32 v102, v66, v102, v67 bitop3:0x36
	v_lshl_add_u32 v102, v102, 4, v135
	ds_write_b64 v102, v[100:101]
	v_add_u32_e32 v101, 0xffffffbf, v143
	v_sub_u32_e32 v102, 0x41, v143
	v_max_i32_e32 v102, v101, v102
	v_subrev_u32_e32 v103, 64, v143
	v_cvt_f32_u32_e32 v102, v102
	v_cmp_gt_i32_e32 vcc, 0, v103
	v_sub_u32_e32 v119, 64, v143
	v_max_i32_e32 v119, v103, v119
	v_cndmask_b32_e32 v100, v105, v104, vcc
	v_cmp_gt_i32_e32 vcc, 0, v101
	v_sub_u32_e32 v103, 0x42, v143
	v_cvt_f32_u32_e32 v119, v119
	v_cndmask_b32_e32 v101, v105, v104, vcc
	v_mul_f32_e32 v101, v101, v102
	v_add_u32_e32 v102, 0xffffffbe, v143
	v_max_i32_e32 v103, v102, v103
	v_cvt_f32_u32_e32 v103, v103
	v_cmp_gt_i32_e32 vcc, 0, v102
	v_mul_f32_e32 v100, v100, v119
	v_sub_u32_e32 v119, 0x43, v143
	v_cndmask_b32_e32 v102, v105, v104, vcc
	v_mul_f32_e32 v102, v102, v103
	v_add_u32_e32 v103, 0xffffffbd, v143
	v_max_i32_e32 v119, v103, v119
	v_cvt_f32_u32_e32 v119, v119
	v_cmp_gt_i32_e32 vcc, 0, v103
	v_exp_f32_e32 v100, v100
	v_exp_f32_e32 v101, v101
	v_cndmask_b32_e32 v103, v105, v104, vcc
	v_exp_f32_e32 v102, v102
	v_mul_f32_e32 v103, v103, v119
	v_exp_f32_e32 v103, v103
	v_mul_f32_e32 v96, v100, v96
	v_mul_f32_e32 v97, v101, v97
	v_mul_f32_e32 v98, v102, v98
	v_mul_f32_e32 v99, v103, v99
	v_cvt_pk_bf16_f32 v96, v96, v97
	v_cvt_pk_bf16_f32 v97, v98, v99
	v_add_u32_e32 v98, 8, v140
	v_bitop3_b32 v98, v66, v98, v67 bitop3:0x36
	v_lshl_add_u32 v98, v98, 4, v135
	ds_write_b64 v98, v[96:97]
	v_add_u32_e32 v97, 0xffffffaf, v143
	v_sub_u32_e32 v98, 0x51, v143
	v_max_i32_e32 v98, v97, v98
	v_add_u32_e32 v99, 0xffffffb0, v143
	v_cvt_f32_u32_e32 v98, v98
	v_cmp_gt_i32_e32 vcc, 0, v99
	v_sub_u32_e32 v100, 0x50, v143
	v_max_i32_e32 v100, v99, v100
	v_cndmask_b32_e32 v96, v105, v104, vcc
	v_cmp_gt_i32_e32 vcc, 0, v97
	v_sub_u32_e32 v99, 0x52, v143
	v_cvt_f32_u32_e32 v100, v100
	v_cndmask_b32_e32 v97, v105, v104, vcc
	v_mul_f32_e32 v97, v97, v98
	v_add_u32_e32 v98, 0xffffffae, v143
	v_max_i32_e32 v99, v98, v99
	v_cvt_f32_u32_e32 v99, v99
	v_cmp_gt_i32_e32 vcc, 0, v98
	v_mul_f32_e32 v96, v96, v100
	v_sub_u32_e32 v100, 0x53, v143
	v_cndmask_b32_e32 v98, v105, v104, vcc
	v_mul_f32_e32 v98, v98, v99
	v_add_u32_e32 v99, 0xffffffad, v143
	v_max_i32_e32 v100, v99, v100
	v_cvt_f32_u32_e32 v100, v100
	v_cmp_gt_i32_e32 vcc, 0, v99
	v_exp_f32_e32 v96, v96
	v_exp_f32_e32 v97, v97
	v_cndmask_b32_e32 v99, v105, v104, vcc
	v_exp_f32_e32 v98, v98
	v_mul_f32_e32 v99, v99, v100
	v_exp_f32_e32 v99, v99
	v_mul_f32_e32 v88, v96, v88
	v_mul_f32_e32 v89, v97, v89
	v_mul_f32_e32 v90, v98, v90
	v_mul_f32_e32 v91, v99, v91
	v_cvt_pk_bf16_f32 v88, v88, v89
	v_cvt_pk_bf16_f32 v89, v90, v91
	v_add_u32_e32 v90, 10, v140
	v_bitop3_b32 v90, v66, v90, v67 bitop3:0x36
; __device__ __forceinline__ unsigned cvt_pk_bf16(float lo, float hi) { unsigned r; asm volatile("v_cvt_pk_bf16_f32 %0, %1, %2" : "=v"(r) : "v"(lo), "v"(hi)); return r; }
; #define LAS __attribute__((address_space(3)))
; #define LBAR() asm volatile("s_waitcnt lgkmcnt(0)\n\ts_barrier" ::: "memory")
; __device__ __forceinline__ void ret_phase(const Params& P, LAS unsigned char* lds, int tid, int lane, int wave, int bid, int G) {
;     ...
;             for (int mt = 0; mt < 8; ++mt) {
;                 const f32x4 a = sa[mt];
;                 float e[4];
; #pragma unroll
;                 for (int i = 0; i < 4; ++i) { const int m = 16 * mt + 4 * g + i, df = n - m; const float f = __builtin_amdgcn_exp2f(df >= 0 ? lgf2 * (float)df : lgb2 * (float)(-df)); e[i] = a[i] * f; }
;                 u32x2 w; w.x = cvt_pk_bf16(e[0], e[1]); w.y = cvt_pk_bf16(e[2], e[3]);
;                 *(LAS u32x2*)(Pt + off256(n, 2 * mt + (g >> 1)) + 8 * (g & 1)) = w;
;             }
;         }
;         LBAR();
;         u32x4 sfr[4], sbr[4];
; #pragma unroll
;         for (int j = 0; j < 2; ++j) { sfr[2 * j] = fp8x8_to_bf16x8(rsf[j].x, rsf[j].y); sfr[2 * j + 1] = fp8x8_to_bf16x8(rsf[j].z, rsf[j].w);
;             sbr[2 * j] = fp8x8_to_bf16x8(rsb[j].x, rsb[j].y); sbr[2 * j + 1] = fp8x8_to_bf16x8(rsb[j].z, rsb[j].w); }
;     ...
;         if (gc >= 512) {
;             const int k = (gc - 512) >> 5, j = gc & 31;
;             const float cf = exp2f(lgf2 * 128.f * (float)j), cb = exp2f(lgb2 * 128.f * (float)(31 - j)), df32 = exp2f(lgf2 * 4096.f), db32 = exp2f(lgb2 * 4096.f);
;             float wgt = cf;
	v_lshl_add_u32 v90, v90, 4, v135
	ds_write_b64 v90, v[88:89]
	v_add_u32_e32 v89, 0xffffff9f, v143
	v_sub_u32_e32 v90, 0x61, v143
	v_max_i32_e32 v90, v89, v90
	v_add_u32_e32 v91, 0xffffffa0, v143
	v_cvt_f32_u32_e32 v90, v90
	v_cmp_gt_i32_e32 vcc, 0, v91
	v_sub_u32_e32 v96, 0x60, v143
	v_max_i32_e32 v96, v91, v96
	v_cndmask_b32_e32 v88, v105, v104, vcc
	v_cmp_gt_i32_e32 vcc, 0, v89
	v_sub_u32_e32 v91, 0x62, v143
	v_cvt_f32_u32_e32 v96, v96
	v_cndmask_b32_e32 v89, v105, v104, vcc
	v_mul_f32_e32 v89, v89, v90
	v_add_u32_e32 v90, 0xffffff9e, v143
	v_max_i32_e32 v91, v90, v91
	v_cvt_f32_u32_e32 v91, v91
	v_cmp_gt_i32_e32 vcc, 0, v90
	v_mul_f32_e32 v88, v88, v96
	v_sub_u32_e32 v96, 0x63, v143
	v_cndmask_b32_e32 v90, v105, v104, vcc
	v_mul_f32_e32 v90, v90, v91
	v_add_u32_e32 v91, 0xffffff9d, v143
	v_max_i32_e32 v96, v91, v96
	v_cvt_f32_u32_e32 v96, v96
	v_cmp_gt_i32_e32 vcc, 0, v91
	v_exp_f32_e32 v88, v88
	v_exp_f32_e32 v89, v89
	v_cndmask_b32_e32 v91, v105, v104, vcc
	v_exp_f32_e32 v90, v90
	v_mul_f32_e32 v91, v91, v96
	v_exp_f32_e32 v91, v91
	v_mul_f32_e32 v80, v88, v80
	v_mul_f32_e32 v81, v89, v81
	v_mul_f32_e32 v82, v90, v82
	v_mul_f32_e32 v83, v91, v83
	v_cvt_pk_bf16_f32 v80, v80, v81
	v_cvt_pk_bf16_f32 v81, v82, v83
	v_add_u32_e32 v82, 12, v140
	v_bitop3_b32 v82, v66, v82, v67 bitop3:0x36
	v_lshl_add_u32 v82, v82, 4, v135
	ds_write_b64 v82, v[80:81]
	v_add_u32_e32 v81, 0xffffff8f, v143
	v_sub_u32_e32 v82, 0x71, v143
	v_max_i32_e32 v82, v81, v82
	v_add_u32_e32 v83, 0xffffff90, v143
	v_cvt_f32_u32_e32 v82, v82
	v_cmp_gt_i32_e32 vcc, 0, v83
	v_sub_u32_e32 v88, 0x70, v143
	v_max_i32_e32 v88, v83, v88
	v_cndmask_b32_e32 v80, v105, v104, vcc
	v_cmp_gt_i32_e32 vcc, 0, v81
	v_sub_u32_e32 v83, 0x72, v143
	v_cvt_f32_u32_e32 v88, v88
	v_cndmask_b32_e32 v81, v105, v104, vcc
	v_mul_f32_e32 v81, v81, v82
	v_add_u32_e32 v82, 0xffffff8e, v143
	v_max_i32_e32 v83, v82, v83
	v_cvt_f32_u32_e32 v83, v83
	v_cmp_gt_i32_e32 vcc, 0, v82
	v_mul_f32_e32 v80, v80, v88
	v_sub_u32_e32 v88, 0x73, v143
	v_cndmask_b32_e32 v82, v105, v104, vcc
	v_mul_f32_e32 v82, v82, v83
	v_add_u32_e32 v83, 0xffffff8d, v143
	v_max_i32_e32 v88, v83, v88
	v_cvt_f32_u32_e32 v88, v88
	v_cmp_gt_i32_e32 vcc, 0, v83
	s_waitcnt lgkmcnt(7)
	v_mfma_f32_16x16x32_bf16 v[72:75], v[156:159], v[50:53], v[72:75]
	v_exp_f32_e32 v80, v80
	v_cndmask_b32_e32 v83, v105, v104, vcc
	v_exp_f32_e32 v81, v81
	v_exp_f32_e32 v82, v82
	v_mul_f32_e32 v83, v83, v88
	v_exp_f32_e32 v83, v83
	s_nop 1
	v_mul_f32_e32 v72, v80, v72
	v_mul_f32_e32 v73, v81, v73
	v_mul_f32_e32 v74, v82, v74
	v_mul_f32_e32 v75, v83, v75
	v_cvt_pk_bf16_f32 v72, v72, v73
	v_cvt_pk_bf16_f32 v73, v74, v75
	v_add_u32_e32 v74, 14, v140
	v_bitop3_b32 v66, v66, v74, v67 bitop3:0x36
	v_lshl_add_u32 v66, v66, 4, v135
	ds_write_b64 v66, v[72:73]
	s_waitcnt vmcnt(17)
	v_cvt_pk_f32_fp8_e32 v[66:67], v68
	v_cvt_pk_f32_fp8_sdwa v[72:73], v68 src0_sel:WORD_1
	v_cvt_pk_f32_fp8_e32 v[74:75], v69
	v_cvt_pk_f32_fp8_sdwa v[80:81], v69 src0_sel:WORD_1
	s_waitcnt lgkmcnt(0)
	s_barrier
	v_cvt_pk_bf16_f32 v66, v66, v67
	v_cvt_pk_bf16_f32 v67, v72, v73
	v_cvt_pk_bf16_f32 v68, v74, v75
	v_cvt_pk_bf16_f32 v69, v80, v81
	v_cvt_pk_f32_fp8_e32 v[72:73], v70
	v_cvt_pk_f32_fp8_sdwa v[74:75], v70 src0_sel:WORD_1
	v_cvt_pk_f32_fp8_e32 v[80:81], v71
	v_cvt_pk_f32_fp8_sdwa v[82:83], v71 src0_sel:WORD_1
	v_cvt_pk_bf16_f32 v70, v72, v73
	v_cvt_pk_bf16_f32 v71, v74, v75
	v_cvt_pk_bf16_f32 v72, v80, v81
	v_cvt_pk_bf16_f32 v73, v82, v83
	s_waitcnt vmcnt(16)
	v_cvt_pk_f32_fp8_e32 v[74:75], v76
	v_cvt_pk_f32_fp8_sdwa v[80:81], v76 src0_sel:WORD_1
	v_cvt_pk_f32_fp8_e32 v[82:83], v77
	v_cvt_pk_f32_fp8_sdwa v[88:89], v77 src0_sel:WORD_1
	v_cvt_pk_bf16_f32 v74, v74, v75
	v_cvt_pk_bf16_f32 v75, v80, v81
	v_cvt_pk_bf16_f32 v76, v82, v83
	v_cvt_pk_bf16_f32 v77, v88, v89
	v_cvt_pk_f32_fp8_e32 v[80:81], v78
	v_cvt_pk_f32_fp8_sdwa v[82:83], v78 src0_sel:WORD_1
	v_cvt_pk_f32_fp8_e32 v[88:89], v79
	v_cvt_pk_f32_fp8_sdwa v[90:91], v79 src0_sel:WORD_1
	v_cvt_pk_bf16_f32 v78, v80, v81
	v_cvt_pk_bf16_f32 v79, v82, v83
	v_cvt_pk_bf16_f32 v80, v88, v89
	v_cvt_pk_bf16_f32 v81, v90, v91
	s_waitcnt vmcnt(15)
	v_cvt_pk_f32_fp8_e32 v[82:83], v84
	v_cvt_pk_f32_fp8_sdwa v[88:89], v84 src0_sel:WORD_1
	v_cvt_pk_f32_fp8_e32 v[90:91], v85
	v_cvt_pk_f32_fp8_sdwa v[96:97], v85 src0_sel:WORD_1
	v_cvt_pk_bf16_f32 v82, v82, v83
	v_cvt_pk_bf16_f32 v83, v88, v89
	v_cvt_pk_bf16_f32 v84, v90, v91
	v_cvt_pk_bf16_f32 v85, v96, v97
	v_cvt_pk_f32_fp8_e32 v[88:89], v86
	v_cvt_pk_f32_fp8_sdwa v[90:91], v86 src0_sel:WORD_1
	v_cvt_pk_f32_fp8_e32 v[96:97], v87
	v_cvt_pk_f32_fp8_sdwa v[98:99], v87 src0_sel:WORD_1
	v_cvt_pk_bf16_f32 v86, v88, v89
	v_cvt_pk_bf16_f32 v87, v90, v91
	v_cvt_pk_bf16_f32 v88, v96, v97
	s_waitcnt vmcnt(14)
	v_cvt_pk_f32_fp8_e32 v[90:91], v92
	v_cvt_pk_f32_fp8_sdwa v[96:97], v92 src0_sel:WORD_1
	v_cvt_pk_bf16_f32 v89, v98, v99
	v_cvt_pk_f32_fp8_e32 v[98:99], v93
	v_cvt_pk_f32_fp8_sdwa v[100:101], v93 src0_sel:WORD_1
	v_cvt_pk_bf16_f32 v90, v90, v91
	v_cvt_pk_bf16_f32 v91, v96, v97
	v_cvt_pk_f32_fp8_e32 v[96:97], v94
	v_cvt_pk_bf16_f32 v92, v98, v99
	v_cvt_pk_bf16_f32 v93, v100, v101
	v_cvt_pk_f32_fp8_sdwa v[98:99], v94 src0_sel:WORD_1
	v_cvt_pk_f32_fp8_e32 v[100:101], v95
	v_cvt_pk_f32_fp8_sdwa v[102:103], v95 src0_sel:WORD_1
	v_cvt_pk_bf16_f32 v94, v96, v97
	v_cvt_pk_bf16_f32 v95, v98, v99
	v_cvt_pk_bf16_f32 v96, v100, v101
	v_cvt_pk_bf16_f32 v97, v102, v103
	s_cbranch_scc1 .LBB0_391
	s_add_i32 s34, s40, 0xfffffe00
	s_and_b32 s5, s56, 3
	s_lshr_b32 s4, s34, 5
	s_bfe_u32 s27, s26, 0x50002
	s_cmp_lt_u32 s34, 32
	s_cbranch_scc1 .LBB0_388
	v_mul_f32_e32 v98, 0x45800000, v105
	v_cmp_gt_f32_e32 vcc, s52, v98
	v_mul_f32_e32 v99, 0x43000000, v105
	v_cvt_f32_ubyte0_e32 v100, s27
	v_cndmask_b32_e32 v98, 0, v132, vcc
	v_mul_f32_e32 v101, v99, v100
	s_and_b64 s[0:1], vcc, exec
	v_fmac_f32_e32 v98, 0x45800000, v105
	v_cmp_gt_f32_e32 vcc, s52, v101
	v_exp_f32_e32 v98, v98
	s_cselect_b32 s0, 0xffffffc0, 0
	v_cndmask_b32_e32 v101, 0, v132, vcc
	v_fmac_f32_e32 v101, v99, v100
	v_exp_f32_e32 v99, v101
	v_ldexp_f32 v98, v98, s0
	s_and_b64 s[0:1], vcc, exec
	s_cselect_b32 s0, 0xffffffc0, 0
	v_ldexp_f32 v99, v99, s0
	s_lshl_b32 s0, s4, 2
	s_or_b32 s0, s0, s5
	s_add_i32 s18, s0, 60
	s_add_i32 s35, s4, 1

; #define LAS __attribute__((address_space(3)))
; #define RT_LOAD(u_) do { const size_t tokc_ = (size_t)((u_) >> 2) * 128; const int h_ = (u_) & 3; \
;         _Pragma("unroll") for (int i = 0; i < 4; ++i) { const int idx = tid + 512 * i; const size_t src = (tokc_ + (idx >> 4)) * 512 + h_ * 128 + 8 * (idx & 15); \
;             rq[i] = *(const u32x4*)(QR + src); rk[i] = *(const u32x4*)(KR + src); rv[i] = *(const u32x4*)(VR + src); } } while (0)
; __device__ __forceinline__ void ret_phase(const Params& P, LAS unsigned char* lds, int tid, int lane, int wave, int bid, int G) {
;     ...
;         for (int j = 0; j < 2; ++j) { const int idx = tid + 512 * j; const unsigned row = idx >> 3, c8 = idx & 7;
;             *(LAS u32x4*)(Qt + off256(row, 2 * c8)) = sfr[2 * j]; *(LAS u32x4*)(Qt + off256(row, 2 * c8 + 1)) = sfr[2 * j + 1];
;             *(LAS u32x4*)(Kt + off256(row, 2 * c8)) = sbr[2 * j]; *(LAS u32x4*)(Kt + off256(row, 2 * c8 + 1)) = sbr[2 * j + 1]; }
;         if (u + G < RET_UNITS) RT_LOAD(u + G);
.LBB0_391:
	s_add_i32 s26, s26, s3
	s_cmpk_gt_i32 s26, 0x9ff
	s_cselect_b64 s[42:43], -1, 0
	s_and_b64 vcc, exec, s[42:43]
	ds_write_b128 v128, v[66:69]
	ds_write_b128 v129, v[70:73]
	ds_write_b128 v128, v[74:77] offset:32768
	ds_write_b128 v129, v[78:81] offset:32768
	ds_write_b128 v130, v[82:85]
	ds_write_b128 v131, v[86:89]
	ds_write_b128 v130, v[90:93] offset:32768
	ds_write_b128 v131, v[94:97] offset:32768
	s_cbranch_vccnz .LBB0_383
	s_branch .LBB0_383
